# weight-transpose hooks and the phase-0 transposes: item index = wave*n_workgroups + workgroup, so a partial last pass is spread one item per workgroup
# baseline (speedup 1.0000x reference)
; __device__ __forceinline__ int bid_() { int t = blockIdx.x; asm volatile("" : "+s"(t)); return t; }
; __device__ __forceinline__ void prologue_phase(const Params& P, float* L) {
;     ...
;     bf16* W13 = (bf16*)(ws + WS_W13); bf16* W2 = (bf16*)(ws + WS_W2); bf16* WIN = (bf16*)(ws + WS_WIN); bf16* WOUT = (bf16*)(ws + WS_WOUT);
;     float* scr = L + wave * (64 * 65);
;     const int gw = bid_() * 8 + wave, NGW = gridDim.x * 8;
;     constexpr int I_F = 2816, I_LF = 3 * I_F, I_FFN = 4 * I_LF, I_IN = 32 * 101, I_OUT = 32 * 32, I_ALL = I_FFN + 2 * I_IN + 2 * I_OUT;
;     for (int it = gw; it < I_ALL; it += NGW) {
.LBB0_379:
	s_lshl_b32 s18, s2, 3
	v_readfirstlane_b32 s0, v168
	s_lshr_b32 s0, s0, 6
	s_add_u32 s18, s18, s0
	s_load_dword s20, s[38:39], 0x0
	s_waitcnt lgkmcnt(0)
	s_lshr_b32 s18, s20, 1
	s_add_u32 s18, s18, s2
	s_cmp_ge_u32 s18, s20
	s_cselect_b32 s1, s20, 0
	s_sub_u32 s18, s18, s1
	s_mul_i32 s0, s0, s20
	s_add_u32 s18, s18, s0
	s_mov_b32 s19, 6552
	s_mov_b32 s98, 5632
	s_mov_b32 s99, 0
	s_mov_b32 s100, 0xb00
	s_waitcnt lgkmcnt(0)
	s_cmp_eq_u32 s20, 0x100
	s_cselect_b32 s19, s19, 0xa540
	s_cselect_b32 s98, s98, 0x7fffffff
	s_cselect_b32 s99, s99, 0
	s_cselect_b32 s100, s100, 0
	s_lshl_b32 s20, s20, 3

; __device__ __forceinline__ void prologue_phase(const Params& P, float* L) {
;     ...
;     for (int it = gw; it < I_ALL; it += NGW) {
;         int r = it;
;         if (r < I_FFN) {
;             const int lf = r / I_LF, q = r % I_LF, which = q / I_F, item = q % I_F;
;             if (which == 0) transpose_item64(P.ffn_w1 + (size_t)lf * DM * FF, DM, FF, W13 + (size_t)lf * NUP * DM, 1, scr, item, lane);
;             else if (which == 1) transpose_item64(P.ffn_w3 + (size_t)lf * DM * FF, DM, FF, W13 + (size_t)lf * NUP * DM, 2, scr, item, lane);
;             else transpose_item64(P.ffn_w2 + (size_t)lf * FF * DM, FF, DM, W2 + (size_t)lf * DM * FF, 0, scr, item, lane);
;         } else {
;             r -= I_FFN;
;             if (r < 2 * I_IN) { const int l = r / I_IN, item = r % I_IN; transpose_item64(P.w_in + (size_t)l * DM * NIN, DM, NIN, WIN + (size_t)l * NINP_W * DM, 3, scr, item, lane); }
;             else { r -= 2 * I_IN; const int l = r / I_OUT, item = r % I_OUT; transpose_item64(P.w_out + (size_t)l * DM * DM, DM, DM, WOUT + (size_t)l * DM * DM, 0, scr, item, lane); }
;         }
;     }
.Lhk_go:
	s_load_dword s21, s[38:39], 0x0
	s_waitcnt lgkmcnt(0)
	s_cmp_eq_u32 s21, 0x100
	s_cbranch_scc0 .Lhk_resume
	s_barrier
	v_readfirstlane_b32 s21, v168
	s_lshr_b32 s21, s21, 6
	s_cmp_ge_u32 s21, s3
	s_cbranch_scc1 .Lhk_resume
	s_sub_u32 s18, s2, s0
	s_mul_i32 s22, s21, s1
	s_add_u32 s18, s18, s22
	s_mul_i32 s20, s1, s3
	s_branch .Ltr_entry
